# hot loop heads (3 GEMM K-loops, diff loop, retention loop) aligned to 64 B with .p2align 6
# baseline (speedup 1.0000x reference)
; template <class Epi, bool ALIGN_EPI>
; __device__ __forceinline__ void gemm_phase(LAS unsigned char* lds, const Gemm g, const StaticOrder& S, const Epi& E, const int wid) {
;     ...
;     for (;;) {
;         const bool has_next = S.next(ui + 1, nxt);
;         const char* nA = has_next ? (const char*)g.A + (size_t)nxt.pm * tstep : cA; const char* nB = has_next ? (const char*)g.Bt + (size_t)nxt.pn * tstep : cB;
;         for (int t = 0; t < nt; t += 2) {
;             const bool last = (t == nt - 2);
;             const char* a1 = cA + (size_t)(t + 1) * kstep;
;             const char* a2 = last ? nA : cA + (size_t)(t + 2) * kstep; const char* b2 = last ? nB : cB + (size_t)(t + 2) * kstep;
;             const char* a3 = a2 + kstep; const char* b3 = b2 + kstep;
;     ...
; #pragma unroll
;         for (int a = 0; a < 2; ++a)
; #pragma unroll
;             for (int b = 0; b < 2; ++b)
; #pragma unroll
;                 for (int m = 0; m < 4; ++m)
; #pragma unroll
;                     for (int n = 0; n < 2; ++n) acc[a][b][m][n] = (f32x4){0.f, 0.f, 0.f, 0.f};
.LBB0_104:
	s_ashr_i32 s39, s38, 31
	s_lshl_b64 s[40:41], s[38:39], 20
	s_add_u32 s40, s55, s40
	s_addc_u32 s41, s56, s41
	s_and_b64 s[42:43], s[4:5], exec
	s_cselect_b32 s39, s41, s3
	s_cselect_b32 s70, s40, s2
	s_ashr_i32 s37, s36, 31
	s_lshl_b64 s[42:43], s[36:37], 20
	s_add_u32 s42, s28, s42
	s_addc_u32 s43, s29, s43
	s_and_b64 s[48:49], s[4:5], exec
	s_cselect_b32 s37, s43, s7
	s_cselect_b32 s71, s42, s6
	s_add_u32 s72, s6, 0x100
	v_mov_b32_e32 v0, 0
	s_addc_u32 s73, s7, 0
	s_mov_b32 s74, -2
	v_mov_b32_e32 v1, v0
	v_mov_b32_e32 v2, v0
	v_mov_b32_e32 v3, v0
	v_mov_b32_e32 v4, v0
	v_mov_b32_e32 v5, v0
	v_mov_b32_e32 v6, v0
	v_mov_b32_e32 v7, v0
	v_mov_b32_e32 v16, v0
	v_mov_b32_e32 v17, v0
	v_mov_b32_e32 v18, v0
	v_mov_b32_e32 v19, v0
	v_mov_b32_e32 v20, v0
	v_mov_b32_e32 v21, v0
	v_mov_b32_e32 v22, v0
	v_mov_b32_e32 v23, v0
	v_mov_b32_e32 v32, v0
	v_mov_b32_e32 v33, v0
	v_mov_b32_e32 v34, v0
	v_mov_b32_e32 v35, v0
	v_mov_b32_e32 v36, v0
	v_mov_b32_e32 v37, v0
	v_mov_b32_e32 v38, v0
	v_mov_b32_e32 v39, v0
	v_mov_b32_e32 v48, v0
	v_mov_b32_e32 v49, v0
	v_mov_b32_e32 v50, v0
	v_mov_b32_e32 v51, v0
	v_mov_b32_e32 v52, v0
	v_mov_b32_e32 v53, v0
	v_mov_b32_e32 v54, v0
	v_mov_b32_e32 v55, v0
	v_mov_b32_e32 v8, v0
	v_mov_b32_e32 v9, v0
	v_mov_b32_e32 v10, v0
	v_mov_b32_e32 v11, v0
	v_mov_b32_e32 v12, v0
	v_mov_b32_e32 v13, v0
	v_mov_b32_e32 v14, v0
	v_mov_b32_e32 v15, v0
	v_mov_b32_e32 v24, v0
	v_mov_b32_e32 v25, v0
	v_mov_b32_e32 v26, v0
	v_mov_b32_e32 v27, v0
	v_mov_b32_e32 v28, v0
	v_mov_b32_e32 v29, v0
	v_mov_b32_e32 v30, v0
	v_mov_b32_e32 v31, v0
	v_mov_b32_e32 v40, v0
	v_mov_b32_e32 v41, v0
	v_mov_b32_e32 v42, v0
	v_mov_b32_e32 v43, v0
	v_mov_b32_e32 v44, v0
	v_mov_b32_e32 v45, v0
	v_mov_b32_e32 v46, v0
	v_mov_b32_e32 v47, v0
	v_mov_b32_e32 v56, v0
	v_mov_b32_e32 v57, v0
	v_mov_b32_e32 v58, v0
	v_mov_b32_e32 v59, v0
	v_mov_b32_e32 v60, v0
	v_mov_b32_e32 v61, v0
	v_mov_b32_e32 v62, v0
	v_mov_b32_e32 v63, v0
	v_mov_b32_e32 v64, v0
	v_mov_b32_e32 v65, v0
	v_mov_b32_e32 v66, v0
	v_mov_b32_e32 v67, v0
	v_mov_b32_e32 v68, v0
	v_mov_b32_e32 v69, v0
	v_mov_b32_e32 v70, v0
	v_mov_b32_e32 v71, v0
	v_mov_b32_e32 v80, v0
	v_mov_b32_e32 v81, v0
	v_mov_b32_e32 v82, v0
	v_mov_b32_e32 v83, v0
	v_mov_b32_e32 v84, v0
	v_mov_b32_e32 v85, v0
	v_mov_b32_e32 v86, v0
	v_mov_b32_e32 v87, v0
	v_mov_b32_e32 v96, v0
	v_mov_b32_e32 v97, v0
	v_mov_b32_e32 v98, v0
	v_mov_b32_e32 v99, v0
	v_mov_b32_e32 v100, v0
	v_mov_b32_e32 v101, v0
	v_mov_b32_e32 v102, v0
	v_mov_b32_e32 v103, v0
	v_mov_b32_e32 v112, v0
	v_mov_b32_e32 v113, v0
	v_mov_b32_e32 v114, v0
	v_mov_b32_e32 v115, v0
	v_mov_b32_e32 v116, v0
	v_mov_b32_e32 v117, v0
	v_mov_b32_e32 v118, v0
	v_mov_b32_e32 v119, v0
	v_mov_b32_e32 v72, v0
	v_mov_b32_e32 v73, v0
	v_mov_b32_e32 v74, v0
	v_mov_b32_e32 v75, v0
	v_mov_b32_e32 v76, v0
	v_mov_b32_e32 v77, v0
	v_mov_b32_e32 v78, v0
	v_mov_b32_e32 v79, v0
	v_mov_b32_e32 v88, v0
	v_mov_b32_e32 v89, v0
	v_mov_b32_e32 v90, v0
	v_mov_b32_e32 v91, v0
	v_mov_b32_e32 v92, v0
	v_mov_b32_e32 v93, v0
	v_mov_b32_e32 v94, v0
	v_mov_b32_e32 v95, v0
	v_mov_b32_e32 v104, v0
	v_mov_b32_e32 v105, v0
	v_mov_b32_e32 v106, v0
	v_mov_b32_e32 v107, v0
	v_mov_b32_e32 v108, v0
	v_mov_b32_e32 v109, v0
	v_mov_b32_e32 v110, v0
	v_mov_b32_e32 v111, v0
	v_mov_b32_e32 v120, v0
	v_mov_b32_e32 v121, v0
	v_mov_b32_e32 v122, v0
	v_mov_b32_e32 v123, v0
	v_mov_b32_e32 v124, v0
	v_mov_b32_e32 v125, v0
	v_mov_b32_e32 v126, v0
	v_mov_b32_e32 v127, v0
	.p2align 6

; #define ATT_WAITBAR_ALL() asm volatile("s_waitcnt vmcnt(0) lgkmcnt(0)\n\ts_barrier" ::: "memory")
; #define ATT_WAITBAR_ONE() do { if (DIFF) asm volatile("s_waitcnt vmcnt(4) lgkmcnt(0)\n\ts_barrier" ::: "memory"); else asm volatile("s_waitcnt vmcnt(3) lgkmcnt(0)\n\ts_barrier" ::: "memory"); } while (0)
; template <bool DIFF>
; __device__ __forceinline__ void attn_item(LAS unsigned char* lds, const bf16_t* Z, bf16_t* MIX, int b, int h, int t, float lam, float shift, const float* gain, int tid, int wid, int lane) {
;     ...
;         if (kt + 1 < nkt) { if (more2) ATT_WAITBAR_ONE(); else ATT_WAITBAR_ALL(); }
;         bcur = bnx;
;     }
.Ldx_b0:
	s_barrier
	s_mov_b32 s15, 1
	.p2align 6

; __device__ __forceinline__ void ret_pair(LAS unsigned char* lds, const bf16_t* Z, bf16_t* MIX, int b, int h, int tA, int tB, const float* gain, int wid) {
;     ...
;         if (kt + 1 < nkt) { if (more2) asm volatile("s_waitcnt vmcnt(3) lgkmcnt(0)\n\ts_barrier" ::: "memory"); else asm volatile("s_waitcnt vmcnt(0) lgkmcnt(0)\n\ts_barrier" ::: "memory"); }
;         bcur = bnx;
.Lrx_b0:
	s_barrier
	s_mov_b32 s98, 1
	s_nop 0
	.p2align 6

; template <class Epi, bool ALIGN_EPI>
; __device__ __forceinline__ void gemm_phase(LAS unsigned char* lds, const Gemm g, const StaticOrder& S, const Epi& E, const int wid) {
;     ...
;     for (;;) {
;         const bool has_next = S.next(ui + 1, nxt);
;         const char* nA = has_next ? (const char*)g.A + (size_t)nxt.pm * tstep : cA; const char* nB = has_next ? (const char*)g.Bt + (size_t)nxt.pn * tstep : cB;
;         for (int t = 0; t < nt; t += 2) {
;             const bool last = (t == nt - 2);
;             const char* a1 = cA + (size_t)(t + 1) * kstep;
;             const char* a2 = last ? nA : cA + (size_t)(t + 2) * kstep; const char* b2 = last ? nB : cB + (size_t)(t + 2) * kstep;
;             const char* a3 = a2 + kstep; const char* b3 = b2 + kstep;
;     ...
; #pragma unroll
;         for (int a = 0; a < 2; ++a)
; #pragma unroll
;             for (int b = 0; b < 2; ++b)
; #pragma unroll
;                 for (int m = 0; m < 4; ++m)
; #pragma unroll
;                     for (int n = 0; n < 2; ++n) acc[a][b][m][n] = (f32x4){0.f, 0.f, 0.f, 0.f};
.LBB0_721:
	s_ashr_i32 s15, s14, 31
	s_lshl_b64 s[16:17], s[14:15], 20
	s_add_u32 s16, s34, s16
	s_addc_u32 s17, s35, s17
	s_and_b64 s[18:19], s[4:5], exec
	s_cselect_b32 s15, s17, s27
	s_cselect_b32 s21, s16, s26
	s_ashr_i32 s13, s12, 31
	s_lshl_b64 s[18:19], s[12:13], 20
	s_add_u32 s18, s36, s18
	s_addc_u32 s19, s37, s19
	s_and_b64 s[28:29], s[4:5], exec
	s_cselect_b32 s13, s19, s25
	s_cselect_b32 s47, s18, s24
	s_add_u32 s48, s24, 0x100
	s_addc_u32 s49, s25, 0
	s_add_u32 s24, s26, 0x80080
	s_addc_u32 s25, s27, 0
	s_add_u32 s50, s26, 0x100
	v_mov_b32_e32 v0, 0
	s_addc_u32 s51, s27, 0
	s_mov_b32 s52, -2
	v_mov_b32_e32 v1, v0
	v_mov_b32_e32 v2, v0
	v_mov_b32_e32 v3, v0
	v_mov_b32_e32 v4, v0
	v_mov_b32_e32 v5, v0
	v_mov_b32_e32 v6, v0
	v_mov_b32_e32 v7, v0
	v_mov_b32_e32 v16, v0
	v_mov_b32_e32 v17, v0
	v_mov_b32_e32 v18, v0
	v_mov_b32_e32 v19, v0
	v_mov_b32_e32 v20, v0
	v_mov_b32_e32 v21, v0
	v_mov_b32_e32 v22, v0
	v_mov_b32_e32 v23, v0
	v_mov_b32_e32 v32, v0
	v_mov_b32_e32 v33, v0
	v_mov_b32_e32 v34, v0
	v_mov_b32_e32 v35, v0
	v_mov_b32_e32 v36, v0
	v_mov_b32_e32 v37, v0
	v_mov_b32_e32 v38, v0
	v_mov_b32_e32 v39, v0
	v_mov_b32_e32 v48, v0
	v_mov_b32_e32 v49, v0
	v_mov_b32_e32 v50, v0
	v_mov_b32_e32 v51, v0
	v_mov_b32_e32 v52, v0
	v_mov_b32_e32 v53, v0
	v_mov_b32_e32 v54, v0
	v_mov_b32_e32 v55, v0
	v_mov_b32_e32 v8, v0
	v_mov_b32_e32 v9, v0
	v_mov_b32_e32 v10, v0
	v_mov_b32_e32 v11, v0
	v_mov_b32_e32 v12, v0
	v_mov_b32_e32 v13, v0
	v_mov_b32_e32 v14, v0
	v_mov_b32_e32 v15, v0
	v_mov_b32_e32 v24, v0
	v_mov_b32_e32 v25, v0
	v_mov_b32_e32 v26, v0
	v_mov_b32_e32 v27, v0
	v_mov_b32_e32 v28, v0
	v_mov_b32_e32 v29, v0
	v_mov_b32_e32 v30, v0
	v_mov_b32_e32 v31, v0
	v_mov_b32_e32 v40, v0
	v_mov_b32_e32 v41, v0
	v_mov_b32_e32 v42, v0
	v_mov_b32_e32 v43, v0
	v_mov_b32_e32 v44, v0
	v_mov_b32_e32 v45, v0
	v_mov_b32_e32 v46, v0
	v_mov_b32_e32 v47, v0
	v_mov_b32_e32 v56, v0
	v_mov_b32_e32 v57, v0
	v_mov_b32_e32 v58, v0
	v_mov_b32_e32 v59, v0
	v_mov_b32_e32 v60, v0
	v_mov_b32_e32 v61, v0
	v_mov_b32_e32 v62, v0
	v_mov_b32_e32 v63, v0
	v_mov_b32_e32 v64, v0
	v_mov_b32_e32 v65, v0
	v_mov_b32_e32 v66, v0
	v_mov_b32_e32 v67, v0
	v_mov_b32_e32 v68, v0
	v_mov_b32_e32 v69, v0
	v_mov_b32_e32 v70, v0
	v_mov_b32_e32 v71, v0
	v_mov_b32_e32 v80, v0
	v_mov_b32_e32 v81, v0
	v_mov_b32_e32 v82, v0
	v_mov_b32_e32 v83, v0
	v_mov_b32_e32 v84, v0
	v_mov_b32_e32 v85, v0
	v_mov_b32_e32 v86, v0
	v_mov_b32_e32 v87, v0
	v_mov_b32_e32 v96, v0
	v_mov_b32_e32 v97, v0
	v_mov_b32_e32 v98, v0
	v_mov_b32_e32 v99, v0
	v_mov_b32_e32 v100, v0
	v_mov_b32_e32 v101, v0
	v_mov_b32_e32 v102, v0
	v_mov_b32_e32 v103, v0
	v_mov_b32_e32 v112, v0
	v_mov_b32_e32 v113, v0
	v_mov_b32_e32 v114, v0
	v_mov_b32_e32 v115, v0
	v_mov_b32_e32 v116, v0
	v_mov_b32_e32 v117, v0
	v_mov_b32_e32 v118, v0
	v_mov_b32_e32 v119, v0
	v_mov_b32_e32 v72, v0
	v_mov_b32_e32 v73, v0
	v_mov_b32_e32 v74, v0
	v_mov_b32_e32 v75, v0
	v_mov_b32_e32 v76, v0
	v_mov_b32_e32 v77, v0
	v_mov_b32_e32 v78, v0
	v_mov_b32_e32 v79, v0
	v_mov_b32_e32 v88, v0
	v_mov_b32_e32 v89, v0
	v_mov_b32_e32 v90, v0
	v_mov_b32_e32 v91, v0
	v_mov_b32_e32 v92, v0
	v_mov_b32_e32 v93, v0
	v_mov_b32_e32 v94, v0
	v_mov_b32_e32 v95, v0
	v_mov_b32_e32 v104, v0
	v_mov_b32_e32 v105, v0
	v_mov_b32_e32 v106, v0
	v_mov_b32_e32 v107, v0
	v_mov_b32_e32 v108, v0
	v_mov_b32_e32 v109, v0
	v_mov_b32_e32 v110, v0
	v_mov_b32_e32 v111, v0
	v_mov_b32_e32 v120, v0
	v_mov_b32_e32 v121, v0
	v_mov_b32_e32 v122, v0
	v_mov_b32_e32 v123, v0
	v_mov_b32_e32 v124, v0
	v_mov_b32_e32 v125, v0
	v_mov_b32_e32 v126, v0
	v_mov_b32_e32 v127, v0
	.p2align 6

; template <class Epi, bool ALIGN_EPI>
; __device__ __forceinline__ void gemm_phase(LAS unsigned char* lds, const Gemm g, const StaticOrder& S, const Epi& E, const int wid) {
;     ...
;     for (;;) {
;         const bool has_next = S.next(ui + 1, nxt);
;         const char* nA = has_next ? (const char*)g.A + (size_t)nxt.pm * tstep : cA; const char* nB = has_next ? (const char*)g.Bt + (size_t)nxt.pn * tstep : cB;
;         for (int t = 0; t < nt; t += 2) {
;             const bool last = (t == nt - 2);
;             const char* a1 = cA + (size_t)(t + 1) * kstep;
;             const char* a2 = last ? nA : cA + (size_t)(t + 2) * kstep; const char* b2 = last ? nB : cB + (size_t)(t + 2) * kstep;
;             const char* a3 = a2 + kstep; const char* b3 = b2 + kstep;
;     ...
; #pragma unroll
;         for (int a = 0; a < 2; ++a)
; #pragma unroll
;             for (int b = 0; b < 2; ++b)
; #pragma unroll
;                 for (int m = 0; m < 4; ++m)
; #pragma unroll
;                     for (int n = 0; n < 2; ++n) acc[a][b][m][n] = (f32x4){0.f, 0.f, 0.f, 0.f};
.LBB0_810:
	s_ashr_i32 s13, s12, 31
	s_lshl_b64 s[14:15], s[12:13], 20
	s_add_u32 s14, s6, s14
	s_addc_u32 s15, s7, s15
	s_and_b64 s[16:17], s[4:5], exec
	s_cselect_b32 s13, s15, s21
	s_cselect_b32 s43, s14, s20
	s_ashr_i32 s11, s10, 31
	s_lshl_b64 s[16:17], s[10:11], 20
	s_add_u32 s16, s26, s16
	s_addc_u32 s17, s27, s17
	s_and_b64 s[22:23], s[4:5], exec
	s_cselect_b32 s11, s17, s19
	s_cselect_b32 s44, s16, s18
	s_add_u32 s45, s18, 0x100
	s_addc_u32 s46, s19, 0
	s_add_u32 s18, s20, 0x80080
	s_addc_u32 s19, s21, 0
	s_add_u32 s47, s20, 0x100
	v_mov_b32_e32 v0, 0
	s_addc_u32 s48, s21, 0
	s_mov_b32 s49, -2
	v_mov_b32_e32 v1, v0
	v_mov_b32_e32 v2, v0
	v_mov_b32_e32 v3, v0
	v_mov_b32_e32 v4, v0
	v_mov_b32_e32 v5, v0
	v_mov_b32_e32 v6, v0
	v_mov_b32_e32 v7, v0
	v_mov_b32_e32 v16, v0
	v_mov_b32_e32 v17, v0
	v_mov_b32_e32 v18, v0
	v_mov_b32_e32 v19, v0
	v_mov_b32_e32 v20, v0
	v_mov_b32_e32 v21, v0
	v_mov_b32_e32 v22, v0
	v_mov_b32_e32 v23, v0
	v_mov_b32_e32 v32, v0
	v_mov_b32_e32 v33, v0
	v_mov_b32_e32 v34, v0
	v_mov_b32_e32 v35, v0
	v_mov_b32_e32 v36, v0
	v_mov_b32_e32 v37, v0
	v_mov_b32_e32 v38, v0
	v_mov_b32_e32 v39, v0
	v_mov_b32_e32 v48, v0
	v_mov_b32_e32 v49, v0
	v_mov_b32_e32 v50, v0
	v_mov_b32_e32 v51, v0
	v_mov_b32_e32 v52, v0
	v_mov_b32_e32 v53, v0
	v_mov_b32_e32 v54, v0
	v_mov_b32_e32 v55, v0
	v_mov_b32_e32 v8, v0
	v_mov_b32_e32 v9, v0
	v_mov_b32_e32 v10, v0
	v_mov_b32_e32 v11, v0
	v_mov_b32_e32 v12, v0
	v_mov_b32_e32 v13, v0
	v_mov_b32_e32 v14, v0
	v_mov_b32_e32 v15, v0
	v_mov_b32_e32 v24, v0
	v_mov_b32_e32 v25, v0
	v_mov_b32_e32 v26, v0
	v_mov_b32_e32 v27, v0
	v_mov_b32_e32 v28, v0
	v_mov_b32_e32 v29, v0
	v_mov_b32_e32 v30, v0
	v_mov_b32_e32 v31, v0
	v_mov_b32_e32 v40, v0
	v_mov_b32_e32 v41, v0
	v_mov_b32_e32 v42, v0
	v_mov_b32_e32 v43, v0
	v_mov_b32_e32 v44, v0
	v_mov_b32_e32 v45, v0
	v_mov_b32_e32 v46, v0
	v_mov_b32_e32 v47, v0
	v_mov_b32_e32 v56, v0
	v_mov_b32_e32 v57, v0
	v_mov_b32_e32 v58, v0
	v_mov_b32_e32 v59, v0
	v_mov_b32_e32 v60, v0
	v_mov_b32_e32 v61, v0
	v_mov_b32_e32 v62, v0
	v_mov_b32_e32 v63, v0
	v_mov_b32_e32 v64, v0
	v_mov_b32_e32 v65, v0
	v_mov_b32_e32 v66, v0
	v_mov_b32_e32 v67, v0
	v_mov_b32_e32 v68, v0
	v_mov_b32_e32 v69, v0
	v_mov_b32_e32 v70, v0
	v_mov_b32_e32 v71, v0
	v_mov_b32_e32 v80, v0
	v_mov_b32_e32 v81, v0
	v_mov_b32_e32 v82, v0
	v_mov_b32_e32 v83, v0
	v_mov_b32_e32 v84, v0
	v_mov_b32_e32 v85, v0
	v_mov_b32_e32 v86, v0
	v_mov_b32_e32 v87, v0
	v_mov_b32_e32 v96, v0
	v_mov_b32_e32 v97, v0
	v_mov_b32_e32 v98, v0
	v_mov_b32_e32 v99, v0
	v_mov_b32_e32 v100, v0
	v_mov_b32_e32 v101, v0
	v_mov_b32_e32 v102, v0
	v_mov_b32_e32 v103, v0
	v_mov_b32_e32 v112, v0
	v_mov_b32_e32 v113, v0
	v_mov_b32_e32 v114, v0
	v_mov_b32_e32 v115, v0
	v_mov_b32_e32 v116, v0
	v_mov_b32_e32 v117, v0
	v_mov_b32_e32 v118, v0
	v_mov_b32_e32 v119, v0
	v_mov_b32_e32 v72, v0
	v_mov_b32_e32 v73, v0
	v_mov_b32_e32 v74, v0
	v_mov_b32_e32 v75, v0
	v_mov_b32_e32 v76, v0
	v_mov_b32_e32 v77, v0
	v_mov_b32_e32 v78, v0
	v_mov_b32_e32 v79, v0
	v_mov_b32_e32 v88, v0
	v_mov_b32_e32 v89, v0
	v_mov_b32_e32 v90, v0
	v_mov_b32_e32 v91, v0
	v_mov_b32_e32 v92, v0
	v_mov_b32_e32 v93, v0
	v_mov_b32_e32 v94, v0
	v_mov_b32_e32 v95, v0
	v_mov_b32_e32 v104, v0
	v_mov_b32_e32 v105, v0
	v_mov_b32_e32 v106, v0
	v_mov_b32_e32 v107, v0
	v_mov_b32_e32 v108, v0
	v_mov_b32_e32 v109, v0
	v_mov_b32_e32 v110, v0
	v_mov_b32_e32 v111, v0
	v_mov_b32_e32 v120, v0
	v_mov_b32_e32 v121, v0
	v_mov_b32_e32 v122, v0
	v_mov_b32_e32 v123, v0
	v_mov_b32_e32 v124, v0
	v_mov_b32_e32 v125, v0
	v_mov_b32_e32 v126, v0
	v_mov_b32_e32 v127, v0
	.p2align 6
